# barrier leader no longer waits for the acknowledgement of its release atomic before resuming
# speedup vs baseline: 1.0096x; 1.0096x over previous
; DEVI unsigned xb_ld(unsigned* p) { return __hip_atomic_load(p, __ATOMIC_RELAXED, __HIP_MEMORY_SCOPE_AGENT); }
; DEVI unsigned xb_add(unsigned* p, unsigned v) { return __hip_atomic_fetch_add(p, v, __ATOMIC_RELAXED, __HIP_MEMORY_SCOPE_AGENT); }
; #define XB_SPIN(cond, bar) do { unsigned _sp = 0; while (cond) { __builtin_amdgcn_s_sleep(1); \
;     if ((++_sp & 255u) == 0u) { if (xb_ld(&(bar)[XB_TMO])) break; if (_sp > XB_SPIN_CAP) { atomicAdd(&(bar)[XB_TMO], 1u); break; } } } } while (0)
; DEVI void xcd_barrier(const XcdBarrier& b) {
;     ...
;       __builtin_amdgcn_fence(__ATOMIC_ACQUIRE, "agent");
;       xb_add(&bar[XB_XGEN(b.x)], 1u);
;       asm volatile("s_waitcnt vmcnt(0)" ::: "memory");
;     } else {
;       XB_SPIN(xb_ld(&bar[XB_XGEN(b.x)]) == gen, bar);
;       __builtin_amdgcn_fence(__ATOMIC_ACQUIRE, "agent");
;       asm volatile("s_waitcnt vmcnt(0)" ::: "memory");
;     }
;   }
;   __syncthreads();
.LBB0_10:
	s_or_b64 exec, exec, s[38:39]
.LBB0_11:
	s_or_b64 exec, exec, s[4:5]
	s_waitcnt lgkmcnt(0)
	s_barrier
